# GLA scan: state image packed with single v_cvt_pk_bf16_f32 per pair, on top of the GLA drain removal
# speedup vs baseline: 1.0135x; 1.0033x over previous
; DI void gla_scan_item(const P& p, int seq, unsigned char* smem) {
;     ...
;     auto loadr = [&](GlaRegs& R, int c) {
;         if (c >= 72) return;
;         { const int pos = tid >> 4, ch = tid & 15; R.rv = *(const u32x4*)(S + (size_t)prow(b, dir, 32 * c + pos) * NP + C_GLA_V + 128 * h + 8 * ch); }
;         { const int t2 = tid & 255, pos = t2 >> 3, ch = t2 & 7; const bf16_t* src = (tid < 256 ? QT : KO) + ((size_t)seq * PT + 32 * c + pos) * 64 + 8 * ch; R.rq = __builtin_nontemporal_load((const u32x4*)src); }
;         if (tid < 128) { const int i = tid >> 2, ch = tid & 3; R.ra = __builtin_nontemporal_load((const u32x4*)(AT + (((size_t)seq * 72 + c) * 32 + i) * 32 + 8 * ch)); }
;     ...
;     auto compute = [&](int c) {
;         const unsigned char* base = smem + (c & 1) * BUFB;
;         const bf16_t* sat = (const bf16_t*)base; const bf16_t* sqt = (const bf16_t*)(base + 2560); const bf16_t* sko = (const bf16_t*)(base + 2560 + 4608); const bf16_t* sv = (const bf16_t*)(base + 2560 + 9216); const float* sdc = (const float*)(base + 2560 + 9216 + 8704);
;         const int dv0 = 16 * w;
;         const bf16x8 vb = tr2(sv + (8 * g + q4) * 136 + dv0 + 4 * p4, sv + (8 * g + 4 + q4) * 136 + dv0 + 4 * p4);
;         bf16x8 bs[2];
;         bs[0] = packacc(st[0], st[1]); bs[1] = packacc(st[2], st[3]);
; #pragma unroll
;         for (int mt = 0; mt < 2; ++mt) {
;             f32x4 acc = (f32x4){0.f, 0.f, 0.f, 0.f};
;             acc = mfma16(vb, ld8(sat + (16 * mt + l15) * 40 + 8 * g), acc);
; #pragma unroll
;             for (int ks = 0; ks < 2; ++ks) {
;                 const bf16_t* r0 = sqt + (16 * mt + l15) * 72 + 32 * ks + 4 * g;
;                 acc = mfma16(bs[ks], ld4x2(r0, r0 + 16), acc);
;             }
;             bf16_t* ob = OG + (size_t)prow(b, dir, 32 * c) * 512 + 128 * h;
;             u32x2 ov; ov.x = pk2(acc[0], acc[1]); ov.y = pk2(acc[2], acc[3]);
;             *(u32x2*)(ob + sgn * ((16 * mt + l15) * 512) + dv0 + 4 * g) = ov;
;         }
; #pragma unroll
;         for (int dt = 0; dt < 4; ++dt) {
;             const bf16x8 ak = tr2(sko + (8 * g + q4) * 72 + 16 * dt + 4 * p4, sko + (8 * g + 4 + q4) * 72 + 16 * dt + 4 * p4);
; #pragma unroll
;             for (int r = 0; r < 4; ++r) st[dt][r] *= sdc[16 * dt + 4 * g + r];
;             st[dt] = mfma16(ak, vb, st[dt]);
;         }
;     };
.LBB0_590:
	ds_read_b64_tr_b16 v[200:201], v123 offset:11776
	ds_read_b64_tr_b16 v[202:203], v124 offset:11776
	ds_read_b128 v[204:207], v125
	ds_read_b128 v[216:219], v127
	ds_read_b64_tr_b16 v[238:239], v144 offset:7168
	ds_read_b64_tr_b16 v[242:243], v144 offset:7200
	ds_read_b64_tr_b16 v[236:237], v143 offset:7168
	ds_read_b64_tr_b16 v[240:241], v143 offset:7200
	ds_read_b64_tr_b16 v[248:249], v143 offset:7232
	ds_read_b64_tr_b16 v[250:251], v144 offset:7232
	v_cvt_pk_bf16_f32 v96, v84, v85
	v_cvt_pk_bf16_f32 v99, v78, v79
	v_add_u32_e32 v152, 0x800, v126
	ds_read2_b64 v[208:211], v152 offset0:64 offset1:68
	ds_read2_b64 v[212:215], v152 offset0:72 offset1:76
	v_cvt_pk_bf16_f32 v98, v76, v77
	v_cvt_pk_bf16_f32 v97, v86, v87
	s_sub_i32 s4, s26, 64
	s_add_i32 s5, s26, 0xfffffec0
	s_add_i32 s6, s27, 0xa0
	s_add_i32 s7, s27, 0xfffff8a0
	s_waitcnt lgkmcnt(9)
	v_mfma_f32_16x16x32_bf16 v[92:95], v[200:203], v[204:207], 0
	s_and_b64 s[2:3], s[0:1], exec
	s_cselect_b32 s2, s4, s7
	s_add_i32 s4, s2, s22
	s_and_b64 s[2:3], s[0:1], exec
	s_waitcnt lgkmcnt(1)
	v_mfma_f32_16x16x32_bf16 v[92:95], v[96:99], v[208:211], v[92:95]
	ds_read_b64_tr_b16 v[208:209], v143 offset:7264
	ds_read_b64_tr_b16 v[210:211], v144 offset:7264
	v_cvt_pk_bf16_f32 v156, v72, v73
	v_cvt_pk_bf16_f32 v155, v82, v83
	v_cvt_pk_bf16_f32 v154, v80, v81
	v_cvt_pk_bf16_f32 v157, v74, v75
	s_cselect_b32 s2, s5, s6
	s_add_i32 s5, s2, s21
	s_cmp_lt_u32 s24, 8
	s_cselect_b64 s[36:37], -1, 0
	s_waitcnt lgkmcnt(2)
	v_mfma_f32_16x16x32_bf16 v[92:95], v[154:157], v[212:215], v[92:95]
	s_and_b64 s[2:3], s[36:37], exec
	s_cselect_b32 s2, s4, s5
	s_ashr_i32 s3, s2, 31
	s_lshl_b64 s[42:43], s[2:3], 10
	v_add_u32_e32 v151, 0x800, v142
	ds_read2_b64 v[224:227], v151 offset0:64 offset1:68
	ds_read2_b64 v[228:231], v151 offset0:72 offset1:76
	s_nop 2
	v_cvt_pk_bf16_f32 v92, v92, v93
	v_cvt_pk_bf16_f32 v93, v94, v95
	v_lshl_add_u64 v[94:95], v[100:101], 0, s[42:43]
	global_store_dwordx2 v[94:95], v[92:93], off
	v_mfma_f32_16x16x32_bf16 v[92:95], v[200:203], v[216:219], 0
	v_add_u32_e32 v153, 0x5000, v145
	ds_read2_b32 v[232:233], v153 offset1:1
	s_waitcnt lgkmcnt(2)
	v_mfma_f32_16x16x32_bf16 v[92:95], v[96:99], v[224:227], v[92:95]
	v_add_u32_e32 v158, 0x5040, v145
	ds_read2_b32 v[244:245], v158 offset1:1
	v_add_u32_e32 v161, 0x50c0, v145
	ds_read2_b32 v[212:213], v161 offset1:1
	s_waitcnt lgkmcnt(3)
	v_mfma_f32_16x16x32_bf16 v[92:95], v[154:157], v[228:231], v[92:95]
	v_add_u32_e32 v156, 0x5008, v145
	ds_read2_b32 v[234:235], v156 offset1:1
	v_add_u32_e32 v157, 0x5048, v145
	ds_read2_b32 v[246:247], v157 offset1:1
	v_add_u32_e32 v154, 0x5080, v145
	ds_read2_b32 v[204:205], v154 offset1:1
	s_nop 4
	v_cvt_pk_bf16_f32 v92, v92, v93
	v_cvt_pk_bf16_f32 v93, v94, v95
	v_lshl_add_u64 v[94:95], v[102:103], 0, s[42:43]
	global_store_dwordx2 v[94:95], v[92:93], off
	v_add_u32_e32 v155, 0x5088, v145
	ds_read2_b32 v[206:207], v155 offset1:1
	v_add_u32_e32 v160, 0x50c8, v145
	ds_read2_b32 v[214:215], v160 offset1:1
	s_waitcnt lgkmcnt(7)
	v_pk_mul_f32 v[84:85], v[84:85], v[232:233]
	s_waitcnt lgkmcnt(4)
	v_pk_mul_f32 v[86:87], v[86:87], v[234:235]
	s_nop 1
	v_mfma_f32_16x16x32_bf16 v[84:87], v[236:239], v[200:203], v[84:87]
	v_pk_mul_f32 v[76:77], v[76:77], v[244:245]
	s_waitcnt lgkmcnt(3)
	v_pk_mul_f32 v[78:79], v[78:79], v[246:247]
	s_nop 1
	v_mfma_f32_16x16x32_bf16 v[76:79], v[240:243], v[200:203], v[76:79]
	s_waitcnt lgkmcnt(2)
	v_pk_mul_f32 v[80:81], v[80:81], v[204:205]
	s_waitcnt lgkmcnt(1)
	v_pk_mul_f32 v[82:83], v[82:83], v[206:207]
	s_nop 1
	v_mfma_f32_16x16x32_bf16 v[80:83], v[248:251], v[200:203], v[80:83]
	s_waitcnt vmcnt(11)
	ds_write_b128 v121, v[12:15] offset:32512
	s_waitcnt vmcnt(10)
	ds_write_b128 v122, v[20:23] offset:20736
	v_pk_mul_f32 v[72:73], v[72:73], v[212:213]
	s_waitcnt lgkmcnt(2)
	v_pk_mul_f32 v[74:75], v[74:75], v[214:215]
	s_nop 1
	v_mfma_f32_16x16x32_bf16 v[72:75], v[208:211], v[200:203], v[72:75]
	s_and_saveexec_b64 s[42:43], s[38:39]
	ds_write_b128 v148, v[16:19] offset:20736
	s_or_b64 exec, exec, s[42:43]
	s_and_saveexec_b64 s[42:43], s[40:41]
	ds_write_b32 v149, v116 offset:40704
	s_or_b64 exec, exec, s[42:43]
	s_cmp_gt_u32 s24, 64
	s_waitcnt lgkmcnt(0)
	s_barrier
	s_cbranch_scc1 .LBB0_600
	v_add_u32_e32 v12, 0xa0, v150
	s_movk_i32 s2, 0x100
	v_cmp_gt_i32_e32 vcc, s2, v12
	v_add_u32_e32 v13, 0xffffffa0, v150
	v_mov_b32_e32 v15, s22
	v_cndmask_b32_e32 v14, v174, v175, vcc
	v_add3_u32 v14, v132, v14, s27
	v_cndmask_b32_e32 v12, v13, v12, vcc
	v_mov_b32_e32 v13, s21
	v_add_u32_e32 v14, 0xfffff6c1, v14
	v_cndmask_b32_e32 v13, v13, v15, vcc
	v_cndmask_b32_e64 v12, v14, v12, s[0:1]
	v_add_u32_e32 v12, v12, v13
	s_movk_i32 s2, 0x3800
	v_add_co_u32_e32 v20, vcc, 0x7000, v112
	v_mad_i64_i32 v[12:13], s[2:3], v12, s2, v[104:105]
	s_nop 0
	v_addc_co_u32_e32 v21, vcc, 0, v113, vcc
	global_load_dwordx4 v[12:15], v[12:13], off offset:1024
	s_nop 0
	global_load_dwordx4 v[20:23], v[20:21], off nt
	s_and_saveexec_b64 s[42:43], s[38:39]
	s_cbranch_execz .LBB0_597
	v_lshl_add_u64 v[16:17], v[106:107], 0, s[44:45]
	v_add_co_u32_e32 v16, vcc, 0x1283f000, v16
	s_nop 1
	v_addc_co_u32_e32 v17, vcc, 0, v17, vcc
	global_load_dwordx4 v[16:19], v[16:17], off offset:2048 nt

; DI void gla_scan_item(const P& p, int seq, unsigned char* smem) {
;     ...
;     auto loadr = [&](GlaRegs& R, int c) {
;         if (c >= 72) return;
;         { const int pos = tid >> 4, ch = tid & 15; R.rv = *(const u32x4*)(S + (size_t)prow(b, dir, 32 * c + pos) * NP + C_GLA_V + 128 * h + 8 * ch); }
;         { const int t2 = tid & 255, pos = t2 >> 3, ch = t2 & 7; const bf16_t* src = (tid < 256 ? QT : KO) + ((size_t)seq * PT + 32 * c + pos) * 64 + 8 * ch; R.rq = __builtin_nontemporal_load((const u32x4*)src); }
;         if (tid < 128) { const int i = tid >> 2, ch = tid & 3; R.ra = __builtin_nontemporal_load((const u32x4*)(AT + (((size_t)seq * 72 + c) * 32 + i) * 32 + 8 * ch)); }
;     ...
;     auto compute = [&](int c) {
;         const unsigned char* base = smem + (c & 1) * BUFB;
;         const bf16_t* sat = (const bf16_t*)base; const bf16_t* sqt = (const bf16_t*)(base + 2560); const bf16_t* sko = (const bf16_t*)(base + 2560 + 4608); const bf16_t* sv = (const bf16_t*)(base + 2560 + 9216); const float* sdc = (const float*)(base + 2560 + 9216 + 8704);
;         const int dv0 = 16 * w;
;         const bf16x8 vb = tr2(sv + (8 * g + q4) * 136 + dv0 + 4 * p4, sv + (8 * g + 4 + q4) * 136 + dv0 + 4 * p4);
;         bf16x8 bs[2];
;         bs[0] = packacc(st[0], st[1]); bs[1] = packacc(st[2], st[3]);
; #pragma unroll
;         for (int mt = 0; mt < 2; ++mt) {
;             f32x4 acc = (f32x4){0.f, 0.f, 0.f, 0.f};
;             acc = mfma16(vb, ld8(sat + (16 * mt + l15) * 40 + 8 * g), acc);
; #pragma unroll
;             for (int ks = 0; ks < 2; ++ks) {
;                 const bf16_t* r0 = sqt + (16 * mt + l15) * 72 + 32 * ks + 4 * g;
;                 acc = mfma16(bs[ks], ld4x2(r0, r0 + 16), acc);
;             }
;             bf16_t* ob = OG + (size_t)prow(b, dir, 32 * c) * 512 + 128 * h;
;             u32x2 ov; ov.x = pk2(acc[0], acc[1]); ov.y = pk2(acc[2], acc[3]);
;             *(u32x2*)(ob + sgn * ((16 * mt + l15) * 512) + dv0 + 4 * g) = ov;
;         }
; #pragma unroll
;         for (int dt = 0; dt < 4; ++dt) {
;             const bf16x8 ak = tr2(sko + (8 * g + q4) * 72 + 16 * dt + 4 * p4, sko + (8 * g + 4 + q4) * 72 + 16 * dt + 4 * p4);
; #pragma unroll
;             for (int r = 0; r < 4; ++r) st[dt][r] *= sdc[16 * dt + 4 * g + r];
;             st[dt] = mfma16(ak, vb, st[dt]);
;         }
;     };
.LBB0_600:
	ds_read_b64_tr_b16 v[200:201], v123 offset:32512
	ds_read_b64_tr_b16 v[202:203], v124 offset:32512
	ds_read_b128 v[204:207], v125 offset:20736
	ds_read_b128 v[216:219], v127 offset:20736
	ds_read_b64_tr_b16 v[238:239], v147 offset:27904
	ds_read_b64_tr_b16 v[242:243], v147 offset:27936
	ds_read_b64_tr_b16 v[236:237], v146 offset:27904
	ds_read_b64_tr_b16 v[240:241], v146 offset:27936
	ds_read_b64_tr_b16 v[248:249], v146 offset:27968
	ds_read_b64_tr_b16 v[250:251], v147 offset:27968
	v_cvt_pk_bf16_f32 v96, v84, v85
	v_cvt_pk_bf16_f32 v99, v78, v79
	v_add_u32_e32 v159, 0x5800, v126
	ds_read2_b64 v[208:211], v159 offset0:96 offset1:100
	ds_read2_b64 v[212:215], v159 offset0:104 offset1:108
	v_cvt_pk_bf16_f32 v98, v76, v77
	v_cvt_pk_bf16_f32 v97, v86, v87
	s_waitcnt lgkmcnt(9)
	v_mfma_f32_16x16x32_bf16 v[88:91], v[200:203], v[204:207], 0
	s_sub_i32 s4, s26, 32
	s_add_i32 s5, s26, 0xfffffee0
	s_add_i32 s6, s27, 0x80
	s_add_i32 s7, s27, 0xfffff880
	s_and_b64 s[2:3], s[0:1], exec
	s_waitcnt lgkmcnt(1)
	v_mfma_f32_16x16x32_bf16 v[162:165], v[96:99], v[208:211], v[88:91]
	ds_read_b64_tr_b16 v[208:209], v146 offset:28000
	ds_read_b64_tr_b16 v[210:211], v147 offset:28000
	s_cselect_b32 s2, s4, s7
	s_add_i32 s4, s2, s22
	s_and_b64 s[2:3], s[0:1], exec
	v_cvt_pk_bf16_f32 v90, v72, v73
	v_cvt_pk_bf16_f32 v89, v82, v83
	v_cvt_pk_bf16_f32 v88, v80, v81
	v_cvt_pk_bf16_f32 v91, v74, v75
	s_cselect_b32 s2, s5, s6
	s_add_i32 s5, s2, s21
	s_waitcnt lgkmcnt(2)
	v_mfma_f32_16x16x32_bf16 v[162:165], v[88:91], v[212:215], v[162:165]
	s_and_b64 s[2:3], s[36:37], exec
	s_cselect_b32 s2, s4, s5
	s_ashr_i32 s3, s2, 31
	s_lshl_b64 s[36:37], s[2:3], 10
	s_nop 3
	v_cvt_pk_bf16_f32 v134, v162, v163
	v_cvt_pk_bf16_f32 v135, v164, v165
	v_lshl_add_u64 v[162:163], v[100:101], 0, s[36:37]
	global_store_dwordx2 v[162:163], v[134:135], off
	v_mfma_f32_16x16x32_bf16 v[184:187], v[200:203], v[216:219], 0
	v_add_u32_e32 v162, 0x5800, v142
	ds_read2_b64 v[224:227], v162 offset0:96 offset1:100
	ds_read2_b64 v[228:231], v162 offset0:104 offset1:108
	v_add_u32_e32 v163, 0xa100, v145
	ds_read2_b32 v[232:233], v163 offset1:1
	s_waitcnt lgkmcnt(2)
	v_mfma_f32_16x16x32_bf16 v[96:99], v[96:99], v[224:227], v[184:187]
	s_nop 2
	v_add_u32_e32 v183, 0xa108, v145
	ds_read2_b32 v[234:235], v183 offset1:1
	v_add_u32_e32 v164, 0xa180, v145
	ds_read2_b32 v[204:205], v164 offset1:1
	s_waitcnt lgkmcnt(3)
	v_mfma_f32_16x16x32_bf16 v[88:91], v[88:91], v[228:231], v[96:99]
	v_add_u32_e32 v185, 0xa140, v145
	ds_read2_b32 v[244:245], v185 offset1:1
	v_add_u32_e32 v184, 0xa148, v145
	ds_read2_b32 v[246:247], v184 offset1:1
	v_add_u32_e32 v165, 0xa188, v145
	ds_read2_b32 v[206:207], v165 offset1:1
	s_nop 4
	v_cvt_pk_bf16_f32 v88, v88, v89
	v_cvt_pk_bf16_f32 v89, v90, v91
	v_lshl_add_u64 v[90:91], v[102:103], 0, s[36:37]
	global_store_dwordx2 v[90:91], v[88:89], off
	v_add_u32_e32 v187, 0xa1c0, v145
	ds_read2_b32 v[212:213], v187 offset1:1
	v_add_u32_e32 v186, 0xa1c8, v145
	ds_read2_b32 v[214:215], v186 offset1:1
	s_waitcnt lgkmcnt(7)
	v_pk_mul_f32 v[84:85], v[84:85], v[232:233]
	s_waitcnt lgkmcnt(6)
	v_pk_mul_f32 v[86:87], v[86:87], v[234:235]
	s_nop 1
	v_mfma_f32_16x16x32_bf16 v[88:91], v[236:239], v[200:203], v[84:87]
	s_nop 2
	s_waitcnt lgkmcnt(4)
	v_pk_mul_f32 v[76:77], v[76:77], v[244:245]
	s_waitcnt lgkmcnt(3)
	v_pk_mul_f32 v[78:79], v[78:79], v[246:247]
	s_nop 1
	v_mfma_f32_16x16x32_bf16 v[84:87], v[240:243], v[200:203], v[76:79]
	s_nop 2
	v_pk_mul_f32 v[80:81], v[80:81], v[204:205]
	s_waitcnt lgkmcnt(2)
	v_pk_mul_f32 v[82:83], v[82:83], v[206:207]
	s_nop 1
	v_mfma_f32_16x16x32_bf16 v[76:79], v[248:251], v[200:203], v[80:83]
	s_nop 2
	s_waitcnt vmcnt(11)
	ds_write_b128 v121, v[24:27] offset:11776
	s_waitcnt vmcnt(10)
	ds_write_b128 v122, v[32:35]
	s_waitcnt lgkmcnt(3)
	v_pk_mul_f32 v[72:73], v[72:73], v[212:213]
	s_waitcnt lgkmcnt(2)
	v_pk_mul_f32 v[74:75], v[74:75], v[214:215]
	s_nop 1
	v_mfma_f32_16x16x32_bf16 v[80:83], v[208:211], v[200:203], v[72:75]
	s_and_saveexec_b64 s[36:37], s[38:39]
	ds_write_b128 v148, v[28:31]
	s_or_b64 exec, exec, s[36:37]
	s_and_saveexec_b64 s[36:37], s[40:41]
	ds_write_b32 v149, v117 offset:19968
	s_or_b64 exec, exec, s[36:37]
	s_cmp_gt_u32 s24, 63
	s_waitcnt lgkmcnt(0)
	s_barrier
	s_cbranch_scc1 .LBB0_610
	v_add_u32_e32 v24, 0xc0, v150
	s_movk_i32 s2, 0x100
	v_cmp_gt_i32_e32 vcc, s2, v24
	v_subrev_u32_e32 v25, 64, v150
	v_mov_b32_e32 v27, s22
	v_cndmask_b32_e32 v26, v174, v175, vcc
	v_add3_u32 v26, v132, v26, s27
	v_cndmask_b32_e32 v24, v25, v24, vcc
	v_mov_b32_e32 v25, s21
	v_add_u32_e32 v26, 0xfffff6a1, v26
	v_cndmask_b32_e32 v25, v25, v27, vcc
	v_cndmask_b32_e64 v24, v26, v24, s[0:1]
	v_add_u32_e32 v24, v24, v25
	s_movk_i32 s2, 0x3800
	v_add_co_u32_e32 v32, vcc, 0x8000, v112
	v_mad_i64_i32 v[24:25], s[2:3], v24, s2, v[104:105]
	s_nop 0
	v_addc_co_u32_e32 v33, vcc, 0, v113, vcc
	global_load_dwordx4 v[24:27], v[24:25], off offset:1024
	s_nop 0
	global_load_dwordx4 v[32:35], v[32:33], off nt
	s_and_saveexec_b64 s[36:37], s[38:39]
	s_cbranch_execz .LBB0_607
	v_lshl_add_u64 v[28:29], v[106:107], 0, s[44:45]
	v_add_co_u32_e32 v28, vcc, 0x12840000, v28
	s_nop 1
	v_addc_co_u32_e32 v29, vcc, 0, v29, vcc
	global_load_dwordx4 v[28:31], v[28:29], off nt

; DI void gla_scan_item(const P& p, int seq, unsigned char* smem) {
;     ...
;     auto loadr = [&](GlaRegs& R, int c) {
;         if (c >= 72) return;
;         { const int pos = tid >> 4, ch = tid & 15; R.rv = *(const u32x4*)(S + (size_t)prow(b, dir, 32 * c + pos) * NP + C_GLA_V + 128 * h + 8 * ch); }
;         { const int t2 = tid & 255, pos = t2 >> 3, ch = t2 & 7; const bf16_t* src = (tid < 256 ? QT : KO) + ((size_t)seq * PT + 32 * c + pos) * 64 + 8 * ch; R.rq = __builtin_nontemporal_load((const u32x4*)src); }
;         if (tid < 128) { const int i = tid >> 2, ch = tid & 3; R.ra = __builtin_nontemporal_load((const u32x4*)(AT + (((size_t)seq * 72 + c) * 32 + i) * 32 + 8 * ch)); }
;     ...
;     auto compute = [&](int c) {
;         const unsigned char* base = smem + (c & 1) * BUFB;
;         const bf16_t* sat = (const bf16_t*)base; const bf16_t* sqt = (const bf16_t*)(base + 2560); const bf16_t* sko = (const bf16_t*)(base + 2560 + 4608); const bf16_t* sv = (const bf16_t*)(base + 2560 + 9216); const float* sdc = (const float*)(base + 2560 + 9216 + 8704);
;         const int dv0 = 16 * w;
;         const bf16x8 vb = tr2(sv + (8 * g + q4) * 136 + dv0 + 4 * p4, sv + (8 * g + 4 + q4) * 136 + dv0 + 4 * p4);
;         bf16x8 bs[2];
;         bs[0] = packacc(st[0], st[1]); bs[1] = packacc(st[2], st[3]);
; #pragma unroll
;         for (int mt = 0; mt < 2; ++mt) {
;             f32x4 acc = (f32x4){0.f, 0.f, 0.f, 0.f};
;             acc = mfma16(vb, ld8(sat + (16 * mt + l15) * 40 + 8 * g), acc);
; #pragma unroll
;             for (int ks = 0; ks < 2; ++ks) {
;                 const bf16_t* r0 = sqt + (16 * mt + l15) * 72 + 32 * ks + 4 * g;
;                 acc = mfma16(bs[ks], ld4x2(r0, r0 + 16), acc);
;             }
;             bf16_t* ob = OG + (size_t)prow(b, dir, 32 * c) * 512 + 128 * h;
;             u32x2 ov; ov.x = pk2(acc[0], acc[1]); ov.y = pk2(acc[2], acc[3]);
;             *(u32x2*)(ob + sgn * ((16 * mt + l15) * 512) + dv0 + 4 * g) = ov;
;         }
; #pragma unroll
;         for (int dt = 0; dt < 4; ++dt) {
;             const bf16x8 ak = tr2(sko + (8 * g + q4) * 72 + 16 * dt + 4 * p4, sko + (8 * g + 4 + q4) * 72 + 16 * dt + 4 * p4);
; #pragma unroll
;             for (int r = 0; r < 4; ++r) st[dt][r] *= sdc[16 * dt + 4 * g + r];
;             st[dt] = mfma16(ak, vb, st[dt]);
;         }
;     };
.LBB0_610:
	ds_read_b64_tr_b16 v[200:201], v123 offset:11776
	ds_read_b64_tr_b16 v[202:203], v124 offset:11776
	ds_read_b128 v[204:207], v125
	ds_read2_b64 v[208:211], v152 offset0:64 offset1:68
	ds_read2_b64 v[212:215], v152 offset0:72 offset1:76
	ds_read2_b64 v[216:219], v151 offset0:64 offset1:68
	ds_read_b128 v[224:227], v127
	ds_read2_b64 v[228:231], v151 offset0:72 offset1:76
	ds_read2_b32 v[232:233], v153 offset1:1
	ds_read2_b32 v[234:235], v156 offset1:1
	ds_read_b64_tr_b16 v[238:239], v144 offset:7168
	ds_read_b64_tr_b16 v[242:243], v144 offset:7200
	v_cvt_pk_bf16_f32 v98, v84, v85
	v_cvt_pk_bf16_f32 v97, v90, v91
	v_cvt_pk_bf16_f32 v96, v88, v89
	v_cvt_pk_bf16_f32 v99, v86, v87
	s_waitcnt lgkmcnt(9)
	v_mfma_f32_16x16x32_bf16 v[72:75], v[200:203], v[204:207], 0
	ds_read_b64_tr_b16 v[236:237], v143 offset:7168
	ds_read_b64_tr_b16 v[240:241], v143 offset:7200
	ds_read2_b32 v[244:245], v158 offset1:1
	s_add_i32 s4, s26, 0xffffff00
	s_add_i32 s5, s27, 0x60
	s_add_i32 s6, s27, 0xfffff860
	s_and_b64 s[2:3], s[0:1], exec
	s_cselect_b32 s2, s26, s6
	s_waitcnt lgkmcnt(11)
	v_mfma_f32_16x16x32_bf16 v[72:75], v[96:99], v[208:211], v[72:75]
	ds_read2_b32 v[246:247], v157 offset1:1
	v_cvt_pk_bf16_f32 v190, v80, v81
	v_cvt_pk_bf16_f32 v189, v78, v79
	v_cvt_pk_bf16_f32 v188, v76, v77
	v_cvt_pk_bf16_f32 v191, v82, v83
	s_add_i32 s6, s2, s22
	s_and_b64 s[2:3], s[0:1], exec
	s_cselect_b32 s2, s4, s5
	s_add_i32 s2, s2, s21
	s_cmp_lt_u32 s24, 6
	s_waitcnt lgkmcnt(11)
	v_mfma_f32_16x16x32_bf16 v[72:75], v[188:191], v[212:215], v[72:75]
	ds_read_b64_tr_b16 v[248:249], v143 offset:7232
	s_cselect_b32 s2, s6, s2
	s_ashr_i32 s3, s2, 31
	s_lshl_b64 s[36:37], s[2:3], 10
	s_nop 3
	v_cvt_pk_bf16_f32 v72, v72, v73
	v_cvt_pk_bf16_f32 v73, v74, v75
	v_lshl_add_u64 v[74:75], v[100:101], 0, s[36:37]
	global_store_dwordx2 v[74:75], v[72:73], off
	s_waitcnt lgkmcnt(10)
	v_mfma_f32_16x16x32_bf16 v[72:75], v[200:203], v[224:227], 0
	ds_read_b64_tr_b16 v[250:251], v144 offset:7232
	ds_read2_b32 v[204:205], v154 offset1:1
	v_mfma_f32_16x16x32_bf16 v[72:75], v[96:99], v[216:219], v[72:75]
	s_waitcnt lgkmcnt(11)
	v_mfma_f32_16x16x32_bf16 v[72:75], v[188:191], v[228:231], v[72:75]
	ds_read2_b32 v[206:207], v155 offset1:1
	s_nop 7
	v_cvt_pk_bf16_f32 v72, v72, v73
	v_cvt_pk_bf16_f32 v73, v74, v75
	v_lshl_add_u64 v[74:75], v[102:103], 0, s[36:37]
	global_store_dwordx2 v[74:75], v[72:73], off
	s_waitcnt lgkmcnt(11)
	v_pk_mul_f32 v[72:73], v[88:89], v[232:233]
	ds_read_b64_tr_b16 v[208:209], v143 offset:7264
	s_waitcnt lgkmcnt(11)
	v_pk_mul_f32 v[74:75], v[90:91], v[234:235]
	ds_read_b64_tr_b16 v[210:211], v144 offset:7264
	s_waitcnt lgkmcnt(9)
	v_mfma_f32_16x16x32_bf16 v[88:91], v[236:239], v[200:203], v[72:75]
	ds_read2_b32 v[212:213], v161 offset1:1
	ds_read2_b32 v[214:215], v160 offset1:1
	s_nop 2
	s_waitcnt lgkmcnt(9)
	v_pk_mul_f32 v[72:73], v[84:85], v[244:245]
	s_waitcnt lgkmcnt(8)
	v_pk_mul_f32 v[74:75], v[86:87], v[246:247]
	s_nop 1
	v_mfma_f32_16x16x32_bf16 v[72:75], v[240:243], v[200:203], v[72:75]
	s_waitcnt lgkmcnt(5)
	v_pk_mul_f32 v[76:77], v[76:77], v[204:205]
	s_waitcnt lgkmcnt(4)
	v_pk_mul_f32 v[78:79], v[78:79], v[206:207]
	s_nop 1
	v_mfma_f32_16x16x32_bf16 v[76:79], v[248:251], v[200:203], v[76:79]
	s_waitcnt vmcnt(11)
	ds_write_b128 v121, v[36:39] offset:32512
	s_waitcnt vmcnt(10)
	ds_write_b128 v122, v[44:47] offset:20736
	s_waitcnt lgkmcnt(3)
	v_pk_mul_f32 v[80:81], v[80:81], v[212:213]
	s_waitcnt lgkmcnt(2)
	v_pk_mul_f32 v[82:83], v[82:83], v[214:215]
	s_nop 1
	v_mfma_f32_16x16x32_bf16 v[80:83], v[208:211], v[200:203], v[80:83]
	s_and_saveexec_b64 s[36:37], s[38:39]
	ds_write_b128 v148, v[40:43] offset:20736
	s_or_b64 exec, exec, s[36:37]
	s_and_saveexec_b64 s[36:37], s[40:41]
	ds_write_b32 v149, v118 offset:40704
	s_or_b64 exec, exec, s[36:37]
	s_cmp_gt_u32 s24, 62
	s_waitcnt lgkmcnt(0)
	s_barrier
	s_cbranch_scc1 .LBB0_620
	v_add_u32_e32 v36, 0xe0, v150
	s_movk_i32 s2, 0x100
	v_cmp_gt_i32_e32 vcc, s2, v36
	v_subrev_u32_e32 v37, 32, v150
	v_mov_b32_e32 v39, s22
	v_cndmask_b32_e32 v38, v174, v175, vcc
	v_add3_u32 v38, v132, v38, s27
	v_cndmask_b32_e32 v36, v37, v36, vcc
	v_mov_b32_e32 v37, s21
	v_add_u32_e32 v38, 0xfffff681, v38
	v_cndmask_b32_e32 v37, v37, v39, vcc
	v_cndmask_b32_e64 v36, v38, v36, s[0:1]
	v_add_u32_e32 v36, v36, v37
	s_movk_i32 s2, 0x3800
	v_add_co_u32_e32 v44, vcc, 0x9000, v112
	v_mad_i64_i32 v[36:37], s[2:3], v36, s2, v[104:105]
	s_nop 0
	v_addc_co_u32_e32 v45, vcc, 0, v113, vcc
	global_load_dwordx4 v[36:39], v[36:37], off offset:1024
	s_nop 0
	global_load_dwordx4 v[44:47], v[44:45], off nt
	s_and_saveexec_b64 s[36:37], s[38:39]
	s_cbranch_execz .LBB0_617
	v_lshl_add_u64 v[40:41], v[106:107], 0, s[44:45]
	v_add_co_u32_e32 v40, vcc, 0x12840000, v40
	s_nop 1
	v_addc_co_u32_e32 v41, vcc, 0, v41, vcc
	global_load_dwordx4 v[40:43], v[40:41], off offset:2048 nt

; DI void gla_scan_item(const P& p, int seq, unsigned char* smem) {
;     ...
;     auto loadr = [&](GlaRegs& R, int c) {
;         if (c >= 72) return;
;         { const int pos = tid >> 4, ch = tid & 15; R.rv = *(const u32x4*)(S + (size_t)prow(b, dir, 32 * c + pos) * NP + C_GLA_V + 128 * h + 8 * ch); }
;         { const int t2 = tid & 255, pos = t2 >> 3, ch = t2 & 7; const bf16_t* src = (tid < 256 ? QT : KO) + ((size_t)seq * PT + 32 * c + pos) * 64 + 8 * ch; R.rq = __builtin_nontemporal_load((const u32x4*)src); }
;         if (tid < 128) { const int i = tid >> 2, ch = tid & 3; R.ra = __builtin_nontemporal_load((const u32x4*)(AT + (((size_t)seq * 72 + c) * 32 + i) * 32 + 8 * ch)); }
;     ...
;     auto compute = [&](int c) {
;         const unsigned char* base = smem + (c & 1) * BUFB;
;         const bf16_t* sat = (const bf16_t*)base; const bf16_t* sqt = (const bf16_t*)(base + 2560); const bf16_t* sko = (const bf16_t*)(base + 2560 + 4608); const bf16_t* sv = (const bf16_t*)(base + 2560 + 9216); const float* sdc = (const float*)(base + 2560 + 9216 + 8704);
;         const int dv0 = 16 * w;
;         const bf16x8 vb = tr2(sv + (8 * g + q4) * 136 + dv0 + 4 * p4, sv + (8 * g + 4 + q4) * 136 + dv0 + 4 * p4);
;         bf16x8 bs[2];
;         bs[0] = packacc(st[0], st[1]); bs[1] = packacc(st[2], st[3]);
; #pragma unroll
;         for (int mt = 0; mt < 2; ++mt) {
;             f32x4 acc = (f32x4){0.f, 0.f, 0.f, 0.f};
;             acc = mfma16(vb, ld8(sat + (16 * mt + l15) * 40 + 8 * g), acc);
; #pragma unroll
;             for (int ks = 0; ks < 2; ++ks) {
;                 const bf16_t* r0 = sqt + (16 * mt + l15) * 72 + 32 * ks + 4 * g;
;                 acc = mfma16(bs[ks], ld4x2(r0, r0 + 16), acc);
;             }
;             bf16_t* ob = OG + (size_t)prow(b, dir, 32 * c) * 512 + 128 * h;
;             u32x2 ov; ov.x = pk2(acc[0], acc[1]); ov.y = pk2(acc[2], acc[3]);
;             *(u32x2*)(ob + sgn * ((16 * mt + l15) * 512) + dv0 + 4 * g) = ov;
;         }
; #pragma unroll
;         for (int dt = 0; dt < 4; ++dt) {
;             const bf16x8 ak = tr2(sko + (8 * g + q4) * 72 + 16 * dt + 4 * p4, sko + (8 * g + 4 + q4) * 72 + 16 * dt + 4 * p4);
; #pragma unroll
;             for (int r = 0; r < 4; ++r) st[dt][r] *= sdc[16 * dt + 4 * g + r];
;             st[dt] = mfma16(ak, vb, st[dt]);
;         }
;     };
.LBB0_620:
	ds_read_b64_tr_b16 v[200:201], v123 offset:32512
	ds_read_b64_tr_b16 v[202:203], v124 offset:32512
	ds_read_b128 v[204:207], v125 offset:20736
	ds_read2_b64 v[208:211], v159 offset0:96 offset1:100
	ds_read2_b64 v[212:215], v159 offset0:104 offset1:108
	ds_read2_b64 v[216:219], v162 offset0:96 offset1:100
	ds_read_b128 v[224:227], v127 offset:20736
	ds_read2_b64 v[228:231], v162 offset0:104 offset1:108
	ds_read2_b32 v[232:233], v163 offset1:1
	ds_read2_b32 v[234:235], v183 offset1:1
	ds_read_b64_tr_b16 v[238:239], v147 offset:27904
	ds_read_b64_tr_b16 v[242:243], v147 offset:27936
	v_cvt_pk_bf16_f32 v98, v72, v73
	v_cvt_pk_bf16_f32 v97, v90, v91
	v_cvt_pk_bf16_f32 v96, v88, v89
	v_cvt_pk_bf16_f32 v99, v74, v75
	s_waitcnt lgkmcnt(9)
	v_mfma_f32_16x16x32_bf16 v[92:95], v[200:203], v[204:207], 0
	ds_read_b64_tr_b16 v[236:237], v146 offset:27904
	ds_read_b64_tr_b16 v[240:241], v146 offset:27936
	ds_read2_b32 v[244:245], v185 offset1:1
	s_add_i32 s4, s26, 32
	s_add_i32 s5, s26, 0xffffff20
	s_add_i32 s6, s27, 64
	s_add_i32 s7, s27, 0xfffff840
	s_and_b64 s[2:3], s[0:1], exec
	s_cselect_b32 s2, s4, s7
	s_waitcnt lgkmcnt(11)
	v_mfma_f32_16x16x32_bf16 v[92:95], v[96:99], v[208:211], v[92:95]
	ds_read2_b32 v[246:247], v184 offset1:1
	v_cvt_pk_bf16_f32 v190, v80, v81
	v_cvt_pk_bf16_f32 v189, v78, v79
	v_cvt_pk_bf16_f32 v188, v76, v77
	v_cvt_pk_bf16_f32 v191, v82, v83
	s_add_i32 s4, s2, s22
	s_and_b64 s[2:3], s[0:1], exec
	s_cselect_b32 s2, s5, s6
	s_add_i32 s2, s2, s21
	s_cmp_lt_u32 s24, 5
	s_waitcnt lgkmcnt(11)
	v_mfma_f32_16x16x32_bf16 v[92:95], v[188:191], v[212:215], v[92:95]
	ds_read_b64_tr_b16 v[248:249], v146 offset:27968
	s_cselect_b32 s2, s4, s2
	s_ashr_i32 s3, s2, 31
	s_lshl_b64 s[36:37], s[2:3], 10
	s_nop 3
	v_cvt_pk_bf16_f32 v92, v92, v93
	v_cvt_pk_bf16_f32 v93, v94, v95
	v_lshl_add_u64 v[94:95], v[100:101], 0, s[36:37]
	global_store_dwordx2 v[94:95], v[92:93], off
	s_waitcnt lgkmcnt(10)
	v_mfma_f32_16x16x32_bf16 v[92:95], v[200:203], v[224:227], 0
	ds_read_b64_tr_b16 v[250:251], v147 offset:27968
	ds_read2_b32 v[204:205], v164 offset1:1
	v_mfma_f32_16x16x32_bf16 v[92:95], v[96:99], v[216:219], v[92:95]
	s_waitcnt lgkmcnt(11)
	v_mfma_f32_16x16x32_bf16 v[92:95], v[188:191], v[228:231], v[92:95]
	ds_read2_b32 v[206:207], v165 offset1:1
	s_nop 7
	v_cvt_pk_bf16_f32 v92, v92, v93
	v_cvt_pk_bf16_f32 v93, v94, v95
	v_lshl_add_u64 v[94:95], v[102:103], 0, s[36:37]
	global_store_dwordx2 v[94:95], v[92:93], off
	s_waitcnt lgkmcnt(11)
	v_pk_mul_f32 v[88:89], v[88:89], v[232:233]
	ds_read_b64_tr_b16 v[208:209], v146 offset:28000
	s_waitcnt lgkmcnt(11)
	v_pk_mul_f32 v[90:91], v[90:91], v[234:235]
	ds_read_b64_tr_b16 v[210:211], v147 offset:28000
	s_waitcnt lgkmcnt(9)
	v_mfma_f32_16x16x32_bf16 v[88:91], v[236:239], v[200:203], v[88:91]
	ds_read2_b32 v[212:213], v187 offset1:1
	ds_read2_b32 v[214:215], v186 offset1:1
	s_waitcnt lgkmcnt(9)
	v_pk_mul_f32 v[72:73], v[72:73], v[244:245]
	s_waitcnt lgkmcnt(8)
	v_pk_mul_f32 v[74:75], v[74:75], v[246:247]
	s_nop 1
	v_mfma_f32_16x16x32_bf16 v[72:75], v[240:243], v[200:203], v[72:75]
	s_waitcnt lgkmcnt(5)
	v_pk_mul_f32 v[76:77], v[76:77], v[204:205]
	s_waitcnt lgkmcnt(4)
	v_pk_mul_f32 v[78:79], v[78:79], v[206:207]
	s_nop 1
	v_mfma_f32_16x16x32_bf16 v[76:79], v[248:251], v[200:203], v[76:79]
	s_waitcnt vmcnt(11)
	ds_write_b128 v121, v[48:51] offset:11776
	s_waitcnt vmcnt(10)
	ds_write_b128 v122, v[56:59]
	s_waitcnt lgkmcnt(3)
	v_pk_mul_f32 v[80:81], v[80:81], v[212:213]
	s_waitcnt lgkmcnt(2)
	v_pk_mul_f32 v[82:83], v[82:83], v[214:215]
	s_nop 1
	v_mfma_f32_16x16x32_bf16 v[84:87], v[208:211], v[200:203], v[80:83]
	s_and_saveexec_b64 s[36:37], s[38:39]
	ds_write_b128 v148, v[52:55]
	s_or_b64 exec, exec, s[36:37]
	s_and_saveexec_b64 s[36:37], s[40:41]
	ds_write_b32 v149, v119 offset:19968
	s_or_b64 exec, exec, s[36:37]
	s_cmp_gt_u32 s24, 61
	s_waitcnt lgkmcnt(0)
	s_barrier
	s_cbranch_scc1 .LBB0_630
	v_add_u32_e32 v48, 0x100, v150
	s_movk_i32 s2, 0x100
	v_cmp_gt_i32_e32 vcc, s2, v48
	v_mov_b32_e32 v50, s21
	v_mov_b32_e32 v51, s22
	v_cndmask_b32_e32 v49, v174, v175, vcc
	v_add3_u32 v49, v132, v49, s27
	v_cndmask_b32_e32 v48, v150, v48, vcc
	v_add_u32_e32 v49, 0xfffff661, v49
	v_cndmask_b32_e32 v50, v50, v51, vcc
	v_cndmask_b32_e64 v48, v49, v48, s[0:1]
	v_add_u32_e32 v48, v48, v50
	s_movk_i32 s2, 0x3800
	v_add_co_u32_e32 v56, vcc, 0xa000, v112
	v_mad_i64_i32 v[48:49], s[2:3], v48, s2, v[104:105]
	s_nop 0
	v_addc_co_u32_e32 v57, vcc, 0, v113, vcc
	global_load_dwordx4 v[48:51], v[48:49], off offset:1024
	s_nop 0
	global_load_dwordx4 v[56:59], v[56:57], off nt
	s_and_saveexec_b64 s[36:37], s[38:39]
	s_cbranch_execz .LBB0_627
	v_lshl_add_u64 v[52:53], v[106:107], 0, s[44:45]
	v_add_co_u32_e32 v52, vcc, 0x12841000, v52
	s_nop 1
	v_addc_co_u32_e32 v53, vcc, 0, v53, vcc
	global_load_dwordx4 v[52:55], v[52:53], off nt

; DI void gla_scan_item(const P& p, int seq, unsigned char* smem) {
;     ...
;     auto loadr = [&](GlaRegs& R, int c) {
;         if (c >= 72) return;
;         { const int pos = tid >> 4, ch = tid & 15; R.rv = *(const u32x4*)(S + (size_t)prow(b, dir, 32 * c + pos) * NP + C_GLA_V + 128 * h + 8 * ch); }
;         { const int t2 = tid & 255, pos = t2 >> 3, ch = t2 & 7; const bf16_t* src = (tid < 256 ? QT : KO) + ((size_t)seq * PT + 32 * c + pos) * 64 + 8 * ch; R.rq = __builtin_nontemporal_load((const u32x4*)src); }
;         if (tid < 128) { const int i = tid >> 2, ch = tid & 3; R.ra = __builtin_nontemporal_load((const u32x4*)(AT + (((size_t)seq * 72 + c) * 32 + i) * 32 + 8 * ch)); }
;     ...
;     auto compute = [&](int c) {
;         const unsigned char* base = smem + (c & 1) * BUFB;
;         const bf16_t* sat = (const bf16_t*)base; const bf16_t* sqt = (const bf16_t*)(base + 2560); const bf16_t* sko = (const bf16_t*)(base + 2560 + 4608); const bf16_t* sv = (const bf16_t*)(base + 2560 + 9216); const float* sdc = (const float*)(base + 2560 + 9216 + 8704);
;         const int dv0 = 16 * w;
;         const bf16x8 vb = tr2(sv + (8 * g + q4) * 136 + dv0 + 4 * p4, sv + (8 * g + 4 + q4) * 136 + dv0 + 4 * p4);
;         bf16x8 bs[2];
;         bs[0] = packacc(st[0], st[1]); bs[1] = packacc(st[2], st[3]);
; #pragma unroll
;         for (int mt = 0; mt < 2; ++mt) {
;             f32x4 acc = (f32x4){0.f, 0.f, 0.f, 0.f};
;             acc = mfma16(vb, ld8(sat + (16 * mt + l15) * 40 + 8 * g), acc);
; #pragma unroll
;             for (int ks = 0; ks < 2; ++ks) {
;                 const bf16_t* r0 = sqt + (16 * mt + l15) * 72 + 32 * ks + 4 * g;
;                 acc = mfma16(bs[ks], ld4x2(r0, r0 + 16), acc);
;             }
;             bf16_t* ob = OG + (size_t)prow(b, dir, 32 * c) * 512 + 128 * h;
;             u32x2 ov; ov.x = pk2(acc[0], acc[1]); ov.y = pk2(acc[2], acc[3]);
;             *(u32x2*)(ob + sgn * ((16 * mt + l15) * 512) + dv0 + 4 * g) = ov;
;         }
; #pragma unroll
;         for (int dt = 0; dt < 4; ++dt) {
;             const bf16x8 ak = tr2(sko + (8 * g + q4) * 72 + 16 * dt + 4 * p4, sko + (8 * g + 4 + q4) * 72 + 16 * dt + 4 * p4);
; #pragma unroll
;             for (int r = 0; r < 4; ++r) st[dt][r] *= sdc[16 * dt + 4 * g + r];
;             st[dt] = mfma16(ak, vb, st[dt]);
;         }
;     };
.LBB0_630:
	ds_read_b64_tr_b16 v[200:201], v123 offset:11776
	ds_read_b64_tr_b16 v[202:203], v124 offset:11776
	ds_read_b128 v[204:207], v125
	ds_read2_b64 v[208:211], v152 offset0:64 offset1:68
	ds_read2_b64 v[212:215], v152 offset0:72 offset1:76
	ds_read2_b64 v[216:219], v151 offset0:64 offset1:68
	ds_read_b128 v[224:227], v127
	ds_read2_b64 v[228:231], v151 offset0:72 offset1:76
	ds_read2_b32 v[232:233], v153 offset1:1
	ds_read2_b32 v[234:235], v156 offset1:1
	ds_read_b64_tr_b16 v[238:239], v144 offset:7168
	ds_read_b64_tr_b16 v[242:243], v144 offset:7200
	v_cvt_pk_bf16_f32 v94, v72, v73
	v_cvt_pk_bf16_f32 v93, v90, v91
	v_cvt_pk_bf16_f32 v92, v88, v89
	v_cvt_pk_bf16_f32 v95, v74, v75
	s_waitcnt lgkmcnt(9)
	v_mfma_f32_16x16x32_bf16 v[80:83], v[200:203], v[204:207], 0
	ds_read_b64_tr_b16 v[236:237], v143 offset:7168
	ds_read_b64_tr_b16 v[240:241], v143 offset:7200
	ds_read2_b32 v[244:245], v158 offset1:1
	s_add_i32 s4, s26, 64
	s_add_i32 s5, s26, 0xffffff40
	s_add_i32 s6, s27, 32
	s_add_i32 s7, s27, 0xfffff820
	s_and_b64 s[2:3], s[0:1], exec
	s_cselect_b32 s2, s4, s7
	s_waitcnt lgkmcnt(11)
	v_mfma_f32_16x16x32_bf16 v[80:83], v[92:95], v[208:211], v[80:83]
	ds_read2_b32 v[246:247], v157 offset1:1
	v_cvt_pk_bf16_f32 v190, v84, v85
	v_cvt_pk_bf16_f32 v189, v78, v79
	v_cvt_pk_bf16_f32 v188, v76, v77
	v_cvt_pk_bf16_f32 v191, v86, v87
	s_add_i32 s4, s2, s22
	s_and_b64 s[2:3], s[0:1], exec
	s_cselect_b32 s2, s5, s6
	s_add_i32 s2, s2, s21
	s_cmp_lt_u32 s24, 4
	s_waitcnt lgkmcnt(11)
	v_mfma_f32_16x16x32_bf16 v[80:83], v[188:191], v[212:215], v[80:83]
	ds_read_b64_tr_b16 v[248:249], v143 offset:7232
	s_cselect_b32 s2, s4, s2
	s_ashr_i32 s3, s2, 31
	s_lshl_b64 s[36:37], s[2:3], 10
	s_nop 3
	v_cvt_pk_bf16_f32 v80, v80, v81
	v_cvt_pk_bf16_f32 v81, v82, v83
	v_lshl_add_u64 v[82:83], v[100:101], 0, s[36:37]
	global_store_dwordx2 v[82:83], v[80:81], off
	s_waitcnt lgkmcnt(10)
	v_mfma_f32_16x16x32_bf16 v[80:83], v[200:203], v[224:227], 0
	ds_read_b64_tr_b16 v[250:251], v144 offset:7232
	ds_read2_b32 v[204:205], v154 offset1:1
	v_mfma_f32_16x16x32_bf16 v[80:83], v[92:95], v[216:219], v[80:83]
	s_waitcnt lgkmcnt(11)
	v_mfma_f32_16x16x32_bf16 v[80:83], v[188:191], v[228:231], v[80:83]
	ds_read2_b32 v[206:207], v155 offset1:1
	s_nop 7
	v_cvt_pk_bf16_f32 v80, v80, v81
	v_cvt_pk_bf16_f32 v81, v82, v83
	v_lshl_add_u64 v[82:83], v[102:103], 0, s[36:37]
	global_store_dwordx2 v[82:83], v[80:81], off
	s_waitcnt lgkmcnt(11)
	v_pk_mul_f32 v[80:81], v[88:89], v[232:233]
	ds_read_b64_tr_b16 v[208:209], v143 offset:7264
	s_waitcnt lgkmcnt(11)
	v_pk_mul_f32 v[82:83], v[90:91], v[234:235]
	ds_read_b64_tr_b16 v[210:211], v144 offset:7264
	s_waitcnt lgkmcnt(9)
	v_mfma_f32_16x16x32_bf16 v[92:95], v[236:239], v[200:203], v[80:83]
	ds_read2_b32 v[212:213], v161 offset1:1
	ds_read2_b32 v[214:215], v160 offset1:1
	s_nop 2
	s_waitcnt lgkmcnt(9)
	v_pk_mul_f32 v[72:73], v[72:73], v[244:245]
	s_waitcnt lgkmcnt(8)
	v_pk_mul_f32 v[74:75], v[74:75], v[246:247]
	s_nop 1
	v_mfma_f32_16x16x32_bf16 v[72:75], v[240:243], v[200:203], v[72:75]
	s_waitcnt lgkmcnt(5)
	v_pk_mul_f32 v[76:77], v[76:77], v[204:205]
	s_waitcnt lgkmcnt(4)
	v_pk_mul_f32 v[78:79], v[78:79], v[206:207]
	s_nop 1
	v_mfma_f32_16x16x32_bf16 v[80:83], v[248:251], v[200:203], v[76:79]
	s_nop 2
	s_waitcnt vmcnt(11)
	ds_write_b128 v121, v[60:63] offset:32512
	s_waitcnt vmcnt(10)
	ds_write_b128 v122, v[68:71] offset:20736
	s_waitcnt lgkmcnt(3)
	v_pk_mul_f32 v[84:85], v[84:85], v[212:213]
	s_waitcnt lgkmcnt(2)
	v_pk_mul_f32 v[86:87], v[86:87], v[214:215]
	s_nop 1
	v_mfma_f32_16x16x32_bf16 v[88:91], v[208:211], v[200:203], v[84:87]
	s_and_saveexec_b64 s[36:37], s[38:39]
	ds_write_b128 v148, v[64:67] offset:20736
	s_or_b64 exec, exec, s[36:37]
	s_and_saveexec_b64 s[36:37], s[40:41]
	ds_write_b32 v149, v120 offset:40704
	s_or_b64 exec, exec, s[36:37]
	s_cmp_gt_u32 s24, 60
	s_waitcnt lgkmcnt(0)
	s_barrier
	s_cbranch_scc1 .LBB0_579
	v_add_u32_e32 v60, 0x120, v150
	s_movk_i32 s2, 0x100
	v_cmp_gt_i32_e32 vcc, s2, v60
	v_add_u32_e32 v61, 32, v150
	v_mov_b32_e32 v63, s22
	v_cndmask_b32_e32 v62, v174, v175, vcc
	v_add3_u32 v62, v132, v62, s27
	v_cndmask_b32_e32 v60, v61, v60, vcc
	v_mov_b32_e32 v61, s21
	v_add_u32_e32 v62, 0xfffff641, v62
	v_cndmask_b32_e32 v61, v61, v63, vcc
	v_cndmask_b32_e64 v60, v62, v60, s[0:1]
	v_add_u32_e32 v60, v60, v61
	s_movk_i32 s2, 0x3800
	v_add_co_u32_e32 v68, vcc, 0xb000, v112
	v_mad_i64_i32 v[60:61], s[2:3], v60, s2, v[104:105]
	s_nop 0
	v_addc_co_u32_e32 v69, vcc, 0, v113, vcc
	global_load_dwordx4 v[60:63], v[60:61], off offset:1024
	s_nop 0
	global_load_dwordx4 v[68:71], v[68:69], off nt
	s_and_saveexec_b64 s[36:37], s[38:39]
	s_cbranch_execz .LBB0_637
	v_lshl_add_u64 v[64:65], v[106:107], 0, s[44:45]
	v_add_co_u32_e32 v64, vcc, 0x12841000, v64
	s_nop 1
	v_addc_co_u32_e32 v65, vcc, 0, v65, vcc
	global_load_dwordx4 v[64:67], v[64:65], off offset:2048 nt
